# final-norm phase: row-invariant norm_f gain vector hoisted out of the row loop (loaded once into v100-v131), 8 fewer loads per row
# baseline (speedup 1.0000x reference)
.LBB0_1455:
	v_readlane_b32 s54, v253, 8
	v_lshrrev_b32_e32 v1, 6, v148
	v_readlane_b32 s55, v253, 1
	v_readfirstlane_b32 s40, v1
	v_readlane_b32 s82, v253, 3
	v_readlane_b32 s83, v253, 4
	s_add_u32 s54, s54, s40
	s_lshl_b32 s55, s55, 3
	s_load_dwordx2 s[70:71], s[82:83], 0x100
	s_load_dwordx4 s[72:75], s[82:83], 0xf0
	v_and_b32_e32 v0, 63, v148
	v_lshlrev_b32_e32 v1, 4, v0
	v_and_b32_e32 v3, 7, v0
	v_lshlrev_b32_e32 v3, 2, v3
	v_add_u32_e32 v7, 0x1000, v1
	s_waitcnt lgkmcnt(0)
	s_add_u32 s42, s70, 0xc000000
	s_addc_u32 s43, s71, 0
	s_add_u32 s46, s70, 0x2fc80100
	s_addc_u32 s47, s71, 0
	s_add_u32 s78, s70, 0x21000000
	s_addc_u32 s79, s71, 0
	global_load_dwordx4 v[100:103], v1, s[72:73]
	global_load_dwordx4 v[104:107], v1, s[72:73] offset:1024
	global_load_dwordx4 v[108:111], v1, s[72:73] offset:2048
	global_load_dwordx4 v[112:115], v1, s[72:73] offset:3072
	global_load_dwordx4 v[116:119], v7, s[72:73]
	global_load_dwordx4 v[120:123], v7, s[72:73] offset:1024
	global_load_dwordx4 v[124:127], v7, s[72:73] offset:2048
	global_load_dwordx4 v[128:131], v7, s[72:73] offset:3072
	s_cmp_lt_u32 s54, 0x3000
	s_cbranch_scc0 .Lnf_done

.Lnf_sa7:
	v_pk_mul_f32 v[92:93], v[8:9], v[8:9]
	v_pk_fma_f32 v[92:93], v[10:11], v[10:11], v[92:93]
	v_pk_fma_f32 v[92:93], v[12:13], v[12:13], v[92:93]
	v_pk_fma_f32 v[92:93], v[14:15], v[14:15], v[92:93]
	v_pk_fma_f32 v[92:93], v[16:17], v[16:17], v[92:93]
	v_pk_fma_f32 v[92:93], v[18:19], v[18:19], v[92:93]
	v_pk_fma_f32 v[92:93], v[20:21], v[20:21], v[92:93]
	v_pk_fma_f32 v[92:93], v[22:23], v[22:23], v[92:93]
	v_pk_fma_f32 v[92:93], v[24:25], v[24:25], v[92:93]
	v_pk_fma_f32 v[92:93], v[26:27], v[26:27], v[92:93]
	v_pk_fma_f32 v[92:93], v[28:29], v[28:29], v[92:93]
	v_pk_fma_f32 v[92:93], v[30:31], v[30:31], v[92:93]
	v_pk_fma_f32 v[92:93], v[32:33], v[32:33], v[92:93]
	v_pk_fma_f32 v[92:93], v[34:35], v[34:35], v[92:93]
	v_pk_fma_f32 v[92:93], v[36:37], v[36:37], v[92:93]
	v_pk_fma_f32 v[92:93], v[38:39], v[38:39], v[92:93]
	v_add_f32_e32 v5, v92, v93
	s_nop 1
	v_add_f32_dpp v5, v5, v5 quad_perm:[1,0,3,2] row_mask:0xf bank_mask:0xf bound_ctrl:1
	s_nop 1
	v_add_f32_dpp v5, v5, v5 quad_perm:[2,3,0,1] row_mask:0xf bank_mask:0xf bound_ctrl:1
	s_nop 1
	v_add_f32_dpp v5, v5, v5 row_half_mirror row_mask:0xf bank_mask:0xf bound_ctrl:1
	s_nop 1
	v_add_f32_dpp v5, v5, v5 row_mirror row_mask:0xf bank_mask:0xf bound_ctrl:1
	s_nop 1
	v_readlane_b32 s40, v5, 0
	v_readlane_b32 s41, v5, 16
	v_readlane_b32 s56, v5, 32
	v_readlane_b32 s57, v5, 48
	s_nop 1
	v_mov_b32_e32 v5, s40
	v_add_f32_e32 v5, s41, v5
	v_add_f32_e32 v5, s56, v5
	v_add_f32_e32 v5, s57, v5
	v_mov_b32_e32 v6, 0x358637bd
	v_fmamk_f32 v5, v5, 0x3a000000, v6
	v_rsq_f32_e32 v6, v5
	s_nop 0
	v_pk_mul_f32 v[8:9], v[8:9], v[6:7] op_sel_hi:[1,0]
	v_pk_mul_f32 v[8:9], v[8:9], v[100:101]
	v_pk_mul_f32 v[10:11], v[10:11], v[6:7] op_sel_hi:[1,0]
	v_pk_mul_f32 v[10:11], v[10:11], v[102:103]
	global_store_dwordx4 v1, v[8:11], s[66:67] nt
	v_pk_mul_f32 v[12:13], v[12:13], v[6:7] op_sel_hi:[1,0]
	v_pk_mul_f32 v[12:13], v[12:13], v[104:105]
	v_pk_mul_f32 v[14:15], v[14:15], v[6:7] op_sel_hi:[1,0]
	v_pk_mul_f32 v[14:15], v[14:15], v[106:107]
	global_store_dwordx4 v1, v[12:15], s[66:67] offset:1024 nt
	v_pk_mul_f32 v[16:17], v[16:17], v[6:7] op_sel_hi:[1,0]
	v_pk_mul_f32 v[16:17], v[16:17], v[108:109]
	v_pk_mul_f32 v[18:19], v[18:19], v[6:7] op_sel_hi:[1,0]
	v_pk_mul_f32 v[18:19], v[18:19], v[110:111]
	global_store_dwordx4 v1, v[16:19], s[66:67] offset:2048 nt
	v_pk_mul_f32 v[20:21], v[20:21], v[6:7] op_sel_hi:[1,0]
	v_pk_mul_f32 v[20:21], v[20:21], v[112:113]
	v_pk_mul_f32 v[22:23], v[22:23], v[6:7] op_sel_hi:[1,0]
	v_pk_mul_f32 v[22:23], v[22:23], v[114:115]
	global_store_dwordx4 v1, v[20:23], s[66:67] offset:3072 nt
	v_pk_mul_f32 v[24:25], v[24:25], v[6:7] op_sel_hi:[1,0]
	v_pk_mul_f32 v[24:25], v[24:25], v[116:117]
	v_pk_mul_f32 v[26:27], v[26:27], v[6:7] op_sel_hi:[1,0]
	v_pk_mul_f32 v[26:27], v[26:27], v[118:119]
	global_store_dwordx4 v7, v[24:27], s[66:67] nt
	v_pk_mul_f32 v[28:29], v[28:29], v[6:7] op_sel_hi:[1,0]
	v_pk_mul_f32 v[28:29], v[28:29], v[120:121]
	v_pk_mul_f32 v[30:31], v[30:31], v[6:7] op_sel_hi:[1,0]
	v_pk_mul_f32 v[30:31], v[30:31], v[122:123]
	global_store_dwordx4 v7, v[28:31], s[66:67] offset:1024 nt
	v_pk_mul_f32 v[32:33], v[32:33], v[6:7] op_sel_hi:[1,0]
	v_pk_mul_f32 v[32:33], v[32:33], v[124:125]
	v_pk_mul_f32 v[34:35], v[34:35], v[6:7] op_sel_hi:[1,0]
	v_pk_mul_f32 v[34:35], v[34:35], v[126:127]
	global_store_dwordx4 v7, v[32:35], s[66:67] offset:2048 nt
	v_pk_mul_f32 v[36:37], v[36:37], v[6:7] op_sel_hi:[1,0]
	v_pk_mul_f32 v[36:37], v[36:37], v[128:129]
	v_pk_mul_f32 v[38:39], v[38:39], v[6:7] op_sel_hi:[1,0]
	v_pk_mul_f32 v[38:39], v[38:39], v[130:131]
	global_store_dwordx4 v7, v[36:39], s[66:67] offset:3072 nt
	s_add_u32 s54, s54, s55
	s_cmp_lt_u32 s54, 0x3000
	s_cbranch_scc1 .Lnf_row
